# P3 address folding with the code after P3 kept at the previous byte phase (one 4-byte pad at the phase exit)
# baseline (speedup 1.0000x reference)
.LBB0_616:
	s_nop 0
	v_readlane_b32 s74, v255, 12
	v_readlane_b32 s75, v255, 13
	s_load_dwordx2 s[92:93], s[74:75], 0x88
	v_readlane_b32 s91, v255, 14
	v_readlane_b32 s90, v255, 11
